# LDS bank-conflict lever: K tile XOR swizzle widened from row&7 to row&15 (10 address registers re-derived in the attention pre-loop)
# baseline (speedup 1.0000x reference)
; __device__ __forceinline__ unsigned cvtpk(float lo, float hi) { f32x2_t v = {lo, hi}; bf16x2_t b = __builtin_convertvector(v, bf16x2_t); return __builtin_bit_cast(unsigned, b); }
; __device__ __forceinline__ float bf2f(short v) { return __uint_as_float(((unsigned)(unsigned short)v) << 16); }
; template <bool FAST> __device__ __forceinline__ void attn_dense_body(const bf16_t* __restrict__ Qb, const bf16_t* __restrict__ Kh, const bf16_t* __restrict__ Vh, ...
;     ...
;     const int prow = tid >> 4, chunk = tid & 15, i0 = (chunk & 3) * 8; const bool second = (chunk & 4) != 0;
;     float gq[8];
; #pragma unroll
;     for (int e = 0; e < 8; ++e) gq[e] = qg[chunk * 8 + e];
; #pragma unroll 2
;     for (int p = 0; p < 8; ++p) { const int row = p * 32 + prow;
;       const bf16x8 raw = ld8(Qb + (long)row * LDQ + chunk * 8);
;       float v[8]; float ss = 0.f;
; #pragma unroll
;       for (int e = 0; e < 8; ++e) { v[e] = bf2f(raw[e]); ss += v[e] * v[e]; }
;       ss += __shfl_xor(ss, 1); ss += __shfl_xor(ss, 2); ss += __shfl_xor(ss, 4); ss += __shfl_xor(ss, 8);
;       const float rstd = (FAST ? SCALE * 1.4426950408889634f : 1.0f) / sqrtf(ss * (1.0f / 128.0f) + 1e-6f);
;       const int t = t0 + row, pos = (chunk < 8) ? (t >> 6) : (t & 63);
;       float o8[8];
; #pragma unroll
;       for (int e = 0; e < 8; ++e) v[e] *= rstd * gq[e];
; #pragma unroll
;       for (int e = 0; e < 8; ++e) { const float pr = __shfl_xor(v[e], 4); const f32x2a cs = rtab[pos * 32 + i0 + e];
;         o8[e] = second ? (v[e] * cs.x + pr * cs.y) : (v[e] * cs.x - pr * cs.y); }
;       u32x4 w = {cvtpk(o8[0], o8[1]), cvtpk(o8[2], o8[3]), cvtpk(o8[4], o8[5]), cvtpk(o8[6], o8[7])};
;       *(u32x4*)(lds + KSWZ(row, chunk * 16)) = w; }
.LBB0_428:
	v_add_co_u32_e32 v28, vcc, 0xfff70000, v10
	v_add_u32_e32 v27, s6, v26
	s_nop 0
	v_addc_co_u32_e32 v29, vcc, -1, v11, vcc
	global_load_dwordx4 v[28:31], v[28:29], off
	v_ashrrev_i32_e32 v32, 6, v27
	v_cndmask_b32_e64 v32, v23, v32, s[42:43]
	v_lshl_or_b32 v32, v32, 5, v17
	v_ashrrev_i32_e32 v33, 31, v32
	v_lshl_add_u64 v[44:45], v[32:33], 3, s[38:39]
	global_load_dwordx4 v[32:35], v[44:45], off offset:48
	global_load_dwordx4 v[36:39], v[44:45], off offset:32
	global_load_dwordx4 v[40:43], v[44:45], off offset:16
	s_nop 0
	global_load_dwordx4 v[44:47], v[44:45], off
	v_add_u32_e32 v27, 32, v27
	v_ashrrev_i32_e32 v27, 6, v27
	v_cndmask_b32_e64 v27, v24, v27, s[42:43]
	s_add_i32 s6, s6, 64
	s_cmpk_eq_i32 s6, 0x100
	s_waitcnt vmcnt(4)
	v_and_b32_e32 v55, 0xffff0000, v29
	v_lshlrev_b32_e32 v54, 16, v29
	v_and_b32_e32 v29, 0xffff0000, v28
	v_lshlrev_b32_e32 v28, 16, v28
	v_pk_mul_f32 v[58:59], v[28:29], v[28:29]
	v_pk_mul_f32 v[56:57], v[54:55], v[54:55]
	v_add_f32_e32 v58, v58, v59
	v_and_b32_e32 v49, 0xffff0000, v31
	v_lshlrev_b32_e32 v48, 16, v31
	v_and_b32_e32 v31, 0xffff0000, v30
	v_lshlrev_b32_e32 v30, 16, v30
	v_add_f32_e32 v56, v56, v58
	v_pk_mul_f32 v[52:53], v[30:31], v[30:31]
	v_add_f32_e32 v56, v57, v56
	v_add_f32_e32 v52, v52, v56
	v_pk_mul_f32 v[50:51], v[48:49], v[48:49]
	v_add_f32_e32 v52, v53, v52
	v_add_f32_e32 v50, v50, v52
	v_add_f32_e32 v50, v51, v50
	ds_bpermute_b32 v51, v18, v50
	s_waitcnt lgkmcnt(0)
	v_add_f32_e32 v50, v50, v51
	ds_bpermute_b32 v51, v19, v50
	s_waitcnt lgkmcnt(0)
	v_add_f32_e32 v50, v50, v51
	ds_bpermute_b32 v51, v20, v50
	s_waitcnt lgkmcnt(0)
	v_add_f32_e32 v50, v50, v51
	ds_bpermute_b32 v51, v21, v50
	s_waitcnt lgkmcnt(0)
	v_add_f32_e32 v50, v50, v51
	v_fmamk_f32 v50, v50, 0x3c000000, v204
	v_cmp_gt_f32_e32 vcc, s73, v50
	v_mul_f32_e32 v51, 0x4f800000, v50
	s_nop 0
	v_cndmask_b32_e32 v50, v50, v51, vcc
	v_sqrt_f32_e32 v51, v50
	s_nop 0
	v_add_u32_e32 v52, -1, v51
	v_fma_f32 v53, -v52, v51, v50
	v_cmp_ge_f32_e64 s[44:45], 0, v53
	v_add_u32_e32 v53, 1, v51
	s_nop 0
	v_cndmask_b32_e64 v52, v51, v52, s[44:45]
	v_fma_f32 v51, -v53, v51, v50
	v_cmp_lt_f32_e64 s[44:45], 0, v51
	s_nop 1
	v_cndmask_b32_e64 v51, v52, v53, s[44:45]
	v_mul_f32_e32 v52, 0x37800000, v51
	v_cndmask_b32_e32 v51, v51, v52, vcc
	v_cmp_class_f32_e32 vcc, v50, v205
	s_nop 1
	v_cndmask_b32_e32 v50, v51, v50, vcc
	v_div_scale_f32 v51, s[8:9], v50, v50, s0
	v_rcp_f32_e32 v52, v51
	s_nop 0
	v_fma_f32 v53, -v51, v52, 1.0
	v_fmac_f32_e32 v52, v53, v52
	v_div_scale_f32 v53, vcc, s0, v50, s0
	v_mul_f32_e32 v56, v53, v52
	v_fma_f32 v57, -v51, v56, v53
	v_fmac_f32_e32 v56, v57, v52
	v_fma_f32 v51, -v51, v56, v53
	v_div_fmas_f32 v51, v51, v52, v56
	v_div_fixup_f32 v50, v51, v50, s0
	v_pk_mul_f32 v[52:53], v[6:7], v[50:51] op_sel_hi:[1,0]
	s_nop 0
	v_pk_mul_f32 v[28:29], v[52:53], v[28:29]
	v_pk_mul_f32 v[52:53], v[8:9], v[50:51] op_sel_hi:[1,0]
	s_nop 0
	v_pk_mul_f32 v[52:53], v[52:53], v[54:55]
	v_pk_mul_f32 v[54:55], v[2:3], v[50:51] op_sel_hi:[1,0]
	v_pk_mul_f32 v[50:51], v[4:5], v[50:51] op_sel_hi:[1,0]
	v_pk_mul_f32 v[30:31], v[54:55], v[30:31]
	v_pk_mul_f32 v[48:49], v[50:51], v[48:49]
	ds_bpermute_b32 v50, v20, v28
	ds_bpermute_b32 v51, v20, v29
	s_waitcnt vmcnt(0)
	v_mov_b32_e32 v55, v46
	v_mov_b32_e32 v46, v45
	v_mov_b32_e32 v54, v44
	s_waitcnt lgkmcnt(0)
	v_pk_mul_f32 v[44:45], v[46:47], v[50:51]
	s_nop 0
	v_cndmask_b32_e64 v45, v45, -v45, s[40:41]
	v_cndmask_b32_e64 v44, v44, -v44, s[40:41]
	v_pk_fma_f32 v[28:29], v[54:55], v[28:29], v[44:45]
	ds_bpermute_b32 v44, v20, v52
	ds_bpermute_b32 v45, v20, v53
	v_mov_b32_e32 v47, v42
	v_mov_b32_e32 v42, v41
	v_mov_b32_e32 v46, v40
	v_cvt_pk_bf16_f32 v28, v28, v29
	s_waitcnt lgkmcnt(0)
	v_pk_mul_f32 v[40:41], v[42:43], v[44:45]
	ds_bpermute_b32 v42, v20, v30
	ds_bpermute_b32 v43, v20, v31
	v_mov_b32_e32 v45, v38
	v_mov_b32_e32 v38, v37
	v_mov_b32_e32 v44, v36
	v_cndmask_b32_e64 v41, v41, -v41, s[40:41]
	s_waitcnt lgkmcnt(0)
	v_pk_mul_f32 v[36:37], v[38:39], v[42:43]
	v_mov_b32_e32 v39, v34
	v_cndmask_b32_e64 v37, v37, -v37, s[40:41]
	v_cndmask_b32_e64 v36, v36, -v36, s[40:41]
	v_pk_fma_f32 v[30:31], v[44:45], v[30:31], v[36:37]
	ds_bpermute_b32 v36, v20, v48
	ds_bpermute_b32 v37, v20, v49
	v_mov_b32_e32 v34, v33
	v_mov_b32_e32 v38, v32
	v_cndmask_b32_e64 v40, v40, -v40, s[40:41]
	v_pk_fma_f32 v[40:41], v[46:47], v[52:53], v[40:41]
	s_waitcnt lgkmcnt(0)
	v_pk_mul_f32 v[32:33], v[34:35], v[36:37]
	v_cvt_pk_bf16_f32 v29, v40, v41
	v_cndmask_b32_e64 v33, v33, -v33, s[40:41]
	v_cndmask_b32_e64 v32, v32, -v32, s[40:41]
	v_pk_fma_f32 v[32:33], v[38:39], v[48:49], v[32:33]
	v_cvt_pk_bf16_f32 v30, v30, v31
	v_cvt_pk_bf16_f32 v31, v32, v33
	ds_write_b128 v25, v[28:31]
	global_load_dwordx4 v[28:31], v[10:11], off
	v_lshl_or_b32 v32, v27, 5, v17
	v_ashrrev_i32_e32 v33, 31, v32
	v_lshl_add_u64 v[44:45], v[32:33], 3, s[38:39]
	global_load_dwordx4 v[32:35], v[44:45], off offset:48
	global_load_dwordx4 v[36:39], v[44:45], off offset:32
	global_load_dwordx4 v[40:43], v[44:45], off offset:16
	s_nop 0
	global_load_dwordx4 v[44:47], v[44:45], off
	v_lshl_add_u64 v[10:11], v[10:11], 0, s[4:5]
	s_waitcnt vmcnt(4)
	v_and_b32_e32 v55, 0xffff0000, v29
	v_lshlrev_b32_e32 v54, 16, v29
	v_and_b32_e32 v29, 0xffff0000, v28
	v_lshlrev_b32_e32 v28, 16, v28
	v_pk_mul_f32 v[58:59], v[28:29], v[28:29]
	v_pk_mul_f32 v[56:57], v[54:55], v[54:55]
	v_add_f32_e32 v27, v58, v59
	v_and_b32_e32 v49, 0xffff0000, v31
	v_lshlrev_b32_e32 v48, 16, v31
	v_and_b32_e32 v31, 0xffff0000, v30
	v_lshlrev_b32_e32 v30, 16, v30
	v_add_f32_e32 v27, v56, v27
	v_pk_mul_f32 v[52:53], v[30:31], v[30:31]
	v_add_f32_e32 v27, v57, v27
	v_add_f32_e32 v27, v52, v27
	v_pk_mul_f32 v[50:51], v[48:49], v[48:49]
	v_add_f32_e32 v27, v53, v27
	v_add_f32_e32 v27, v50, v27
	v_add_f32_e32 v27, v51, v27
	ds_bpermute_b32 v50, v18, v27
	s_waitcnt lgkmcnt(0)
; __device__ __forceinline__ unsigned cvtpk(float lo, float hi) { f32x2_t v = {lo, hi}; bf16x2_t b = __builtin_convertvector(v, bf16x2_t); return __builtin_bit_cast(unsigned, b); }
; __device__ __forceinline__ float bf2f(short v) { return __uint_as_float(((unsigned)(unsigned short)v) << 16); }
; __device__ __forceinline__ int v_st(int k, int c) { const int kk = (k & ~0xC) | ((k & 4) << 1) | ((k & 8) >> 1); return ((kk >> 3) * 4 + (c >> 5)) * 512 + ((kk & 7) * 32 + (c & 31)) * 2; }
; __device__ __forceinline__ int v_rd_base(int lane) { return ((lane & 3) << 3) | (((lane >> 2) & 3) << 6) | (((lane >> 4) & 1) << 5) | (((lane >> 5) & 1) << 8); }
; template <bool FAST> __device__ __forceinline__ void attn_dense_body(const bf16_t* __restrict__ Qb, const bf16_t* __restrict__ Kh, const bf16_t* __restrict__ Vh, ...
;     ...
;       for (int e = 0; e < 8; ++e) { v[e] = bf2f(raw[e]); ss += v[e] * v[e]; }
;       ss += __shfl_xor(ss, 1); ss += __shfl_xor(ss, 2); ss += __shfl_xor(ss, 4); ss += __shfl_xor(ss, 8);
;       const float rstd = (FAST ? SCALE * 1.4426950408889634f : 1.0f) / sqrtf(ss * (1.0f / 128.0f) + 1e-6f);
;       const int t = t0 + row, pos = (chunk < 8) ? (t >> 6) : (t & 63);
;       float o8[8];
; #pragma unroll
;       for (int e = 0; e < 8; ++e) v[e] *= rstd * gq[e];
; #pragma unroll
;       for (int e = 0; e < 8; ++e) { const float pr = __shfl_xor(v[e], 4); const f32x2a cs = rtab[pos * 32 + i0 + e];
;         o8[e] = second ? (v[e] * cs.x + pr * cs.y) : (v[e] * cs.x - pr * cs.y); }
;       u32x4 w = {cvtpk(o8[0], o8[1]), cvtpk(o8[2], o8[3]), cvtpk(o8[4], o8[5]), cvtpk(o8[6], o8[7])};
;       *(u32x4*)(lds + KSWZ(row, chunk * 16)) = w; }
;     __syncthreads();
; #pragma unroll
;     for (int d0 = 0; d0 < 8; ++d0) qr[d0] = *reinterpret_cast<const bf16x8*>(lds + KSWZ(wid * QBLK + r32, (d0 * 16 + hi * 8) * 2));
;     __syncthreads();
;   }
;   const int sr = tid >> 4, sc = (tid & 15) * 8, vst0 = v_st(sr, sc), vst1 = v_st(32 + sr, sc);
;   const int vb0 = (int)(uintptr_t)V_lds + v_rd_base(lane);
;   struct { bf16x8 vs0, vs1, ks0, ks1; } sr_[2];
;   const unsigned voff = (unsigned)(sr * LDV + sc) * 2u, koff = (unsigned)(sr * LDKK + sc) * 2u;
	v_add_f32_e32 v27, v27, v50
	ds_bpermute_b32 v50, v19, v27
	s_waitcnt lgkmcnt(0)
	v_add_f32_e32 v27, v27, v50
	ds_bpermute_b32 v50, v20, v27
	s_waitcnt lgkmcnt(0)
	v_add_f32_e32 v27, v27, v50
	ds_bpermute_b32 v50, v21, v27
	s_waitcnt lgkmcnt(0)
	v_add_f32_e32 v27, v27, v50
	v_fmamk_f32 v27, v27, 0x3c000000, v204
	v_cmp_gt_f32_e32 vcc, s73, v27
	v_mul_f32_e32 v50, 0x4f800000, v27
	s_nop 0
	v_cndmask_b32_e32 v27, v27, v50, vcc
	v_sqrt_f32_e32 v50, v27
	s_nop 0
	v_add_u32_e32 v51, -1, v50
	v_fma_f32 v52, -v51, v50, v27
	v_cmp_ge_f32_e64 s[44:45], 0, v52
	v_add_u32_e32 v52, 1, v50
	s_nop 0
	v_cndmask_b32_e64 v51, v50, v51, s[44:45]
	v_fma_f32 v50, -v52, v50, v27
	v_cmp_lt_f32_e64 s[44:45], 0, v50
	s_nop 1
	v_cndmask_b32_e64 v50, v51, v52, s[44:45]
	v_mul_f32_e32 v51, 0x37800000, v50
	v_cndmask_b32_e32 v50, v50, v51, vcc
	v_cmp_class_f32_e32 vcc, v27, v205
	s_nop 1
	v_cndmask_b32_e32 v27, v50, v27, vcc
	v_div_scale_f32 v50, s[8:9], v27, v27, s0
	v_rcp_f32_e32 v51, v50
	s_nop 0
	v_fma_f32 v52, -v50, v51, 1.0
	v_fmac_f32_e32 v51, v52, v51
	v_div_scale_f32 v52, vcc, s0, v27, s0
	v_mul_f32_e32 v53, v52, v51
	v_fma_f32 v56, -v50, v53, v52
	v_fmac_f32_e32 v53, v56, v51
	v_fma_f32 v50, -v50, v53, v52
	v_div_fmas_f32 v50, v50, v51, v53
	v_div_fixup_f32 v50, v50, v27, s0
	v_pk_mul_f32 v[52:53], v[6:7], v[50:51] op_sel_hi:[1,0]
	s_nop 0
	v_pk_mul_f32 v[28:29], v[52:53], v[28:29]
	v_pk_mul_f32 v[52:53], v[8:9], v[50:51] op_sel_hi:[1,0]
	s_nop 0
	v_pk_mul_f32 v[52:53], v[52:53], v[54:55]
	v_pk_mul_f32 v[54:55], v[2:3], v[50:51] op_sel_hi:[1,0]
	v_pk_mul_f32 v[50:51], v[4:5], v[50:51] op_sel_hi:[1,0]
	v_pk_mul_f32 v[30:31], v[54:55], v[30:31]
	v_pk_mul_f32 v[48:49], v[50:51], v[48:49]
	ds_bpermute_b32 v50, v20, v28
	ds_bpermute_b32 v51, v20, v29
	s_waitcnt vmcnt(0)
	v_mov_b32_e32 v55, v46
	v_mov_b32_e32 v46, v45
	v_mov_b32_e32 v54, v44
	s_waitcnt lgkmcnt(0)
	v_pk_mul_f32 v[44:45], v[46:47], v[50:51]
	s_nop 0
	v_cndmask_b32_e64 v45, v45, -v45, s[40:41]
	v_cndmask_b32_e64 v44, v44, -v44, s[40:41]
	v_pk_fma_f32 v[28:29], v[54:55], v[28:29], v[44:45]
	ds_bpermute_b32 v44, v20, v52
	ds_bpermute_b32 v45, v20, v53
	v_mov_b32_e32 v47, v42
	v_mov_b32_e32 v42, v41
	v_mov_b32_e32 v46, v40
	v_cvt_pk_bf16_f32 v28, v28, v29
	s_waitcnt lgkmcnt(0)
	v_pk_mul_f32 v[40:41], v[42:43], v[44:45]
	ds_bpermute_b32 v42, v20, v30
	ds_bpermute_b32 v43, v20, v31
	v_mov_b32_e32 v45, v38
	v_mov_b32_e32 v38, v37
	v_mov_b32_e32 v44, v36
	v_cndmask_b32_e64 v41, v41, -v41, s[40:41]
	s_waitcnt lgkmcnt(0)
	v_pk_mul_f32 v[36:37], v[38:39], v[42:43]
	v_mov_b32_e32 v39, v34
	v_cndmask_b32_e64 v37, v37, -v37, s[40:41]
	v_cndmask_b32_e64 v36, v36, -v36, s[40:41]
	v_pk_fma_f32 v[30:31], v[44:45], v[30:31], v[36:37]
	ds_bpermute_b32 v36, v20, v48
	ds_bpermute_b32 v37, v20, v49
	v_mov_b32_e32 v34, v33
	v_mov_b32_e32 v38, v32
	v_cndmask_b32_e64 v40, v40, -v40, s[40:41]
	v_pk_fma_f32 v[40:41], v[46:47], v[52:53], v[40:41]
	s_waitcnt lgkmcnt(0)
	v_pk_mul_f32 v[32:33], v[34:35], v[36:37]
	v_cvt_pk_bf16_f32 v29, v40, v41
	v_cndmask_b32_e64 v33, v33, -v33, s[40:41]
	v_cndmask_b32_e64 v32, v32, -v32, s[40:41]
	v_pk_fma_f32 v[32:33], v[38:39], v[48:49], v[32:33]
	v_cvt_pk_bf16_f32 v30, v30, v31
	v_cvt_pk_bf16_f32 v31, v32, v33
	ds_write_b128 v25, v[28:31] offset:8192
	v_add_u32_e32 v25, 0x4000, v25
	s_cbranch_scc0 .LBB0_428
	s_lshl_b64 s[6:7], s[50:51], 23
	s_add_u32 s16, s12, s22
	s_addc_u32 s17, s13, s20
	s_add_u32 s8, s10, s6
	s_addc_u32 s9, s11, s7
	s_lshl_b32 s2, s2, 8
	s_add_u32 s8, s8, s2
	s_addc_u32 s9, s9, 0
	s_add_u32 s16, s16, s2
	s_addc_u32 s17, s17, 0
	s_ashr_i32 s2, s55, 6
	s_lshl_b32 s23, s2, 13
	v_lshlrev_b32_e32 v2, 8, v1
	v_and_b32_e32 v23, 0x1f00, v2
	v_lshrrev_b32_e32 v2, 1, v1
	v_lshlrev_b32_e32 v44, 4, v1
	s_add_i32 s23, s23, 0
	v_and_b32_e32 v3, 16, v2
	v_and_b32_e32 v4, 0x70, v44
	v_add_u32_e32 v5, s23, v23
	s_movk_i32 s23, 0x60
	v_bitop3_b32 v17, v2, v4, 16 bitop3:0x6c
	v_bitop3_b32 v34, v3, v4, s23 bitop3:0x36
	s_movk_i32 s23, 0x80
	v_add_u32_e32 v2, v5, v17
	v_bitop3_b32 v32, v3, v4, 32 bitop3:0x36
	v_bitop3_b32 v33, v3, v4, 64 bitop3:0x36
	v_bitop3_b32 v35, v3, v4, s23 bitop3:0x36
	s_movk_i32 s23, 0xa0
	s_waitcnt lgkmcnt(0)
	s_barrier
	v_add_u32_e32 v6, v5, v32
	ds_read_b128 v[144:147], v2
	ds_read_b128 v[140:143], v6
	v_add_u32_e32 v2, v5, v33
	v_bitop3_b32 v36, v3, v4, s23 bitop3:0x36
	s_movk_i32 s23, 0xc0
	v_add_u32_e32 v6, v5, v34
	ds_read_b128 v[136:139], v2
	ds_read_b128 v[132:135], v6
	v_add_u32_e32 v2, v5, v35
	v_bitop3_b32 v37, v3, v4, s23 bitop3:0x36
	s_movk_i32 s23, 0xe0
	v_add_u32_e32 v6, v5, v36
	ds_read_b128 v[128:131], v2
	ds_read_b128 v[124:127], v6
	v_add_u32_e32 v2, v5, v37
	v_bitop3_b32 v45, v3, v4, s23 bitop3:0x36
	v_add_u32_e32 v3, v5, v45
	ds_read_b128 v[120:123], v2
	ds_read_b128 v[116:119], v3
	v_mul_lo_u32 v2, v13, s1
	v_or_b32_e32 v18, v16, v2
	v_mov_b32_e32 v19, v114
	v_lshl_add_u64 v[48:49], s[16:17], 0, v[18:19]
	v_add_co_u32_e32 v2, vcc, s77, v48
	s_mov_b32 s16, 0x94000
	s_nop 0
	v_addc_co_u32_e32 v3, vcc, 0, v49, vcc
	v_add_co_u32_e32 v6, vcc, s16, v48
	v_lshl_or_b32 v20, v13, 10, v16
	s_nop 0
	v_addc_co_u32_e32 v7, vcc, 0, v49, vcc
	v_mov_b32_e32 v21, v114
	s_waitcnt lgkmcnt(0)
	s_barrier
; __device__ __forceinline__ int v_st(int k, int c) { const int kk = (k & ~0xC) | ((k & 4) << 1) | ((k & 8) >> 1); return ((kk >> 3) * 4 + (c >> 5)) * 512 + ((kk & 7) * 32 + (c & 31)) * 2; }
; __device__ __forceinline__ int v_rd_base(int lane) { return ((lane & 3) << 3) | (((lane >> 2) & 3) << 6) | (((lane >> 4) & 1) << 5) | (((lane >> 5) & 1) << 8); }
; #define SLOAD(i, k0) do { const char* vb_ = (const char*)Vh + (size_t)(k0) * (LDV * 2); const char* kb_ = (const char*)Kh + (size_t)(k0) * (LDKK * 2); \
;     sr_[i].vs0 = *(const bf16x8*)(vb_ + voff); sr_[i].vs1 = *(const bf16x8*)(vb_ + 32 * LDV * 2 + voff); \
;     sr_[i].ks0 = *(const bf16x8*)(kb_ + koff); sr_[i].ks1 = *(const bf16x8*)(kb_ + 32 * LDKK * 2 + koff); } while (0)
; #define SWRITE(b, i) do { *(bf16x8*)((char*)V_lds + (b) * SHM_V + vst0) = sr_[i].vs0;          \
;     *(bf16x8*)((char*)V_lds + (b) * SHM_V + vst1) = sr_[i].vs1; int kc = sc * 2;               \
;     *(bf16x8*)((char*)K_lds + (b) * SHM_K + KSWZ(sr, kc)) = sr_[i].ks0;                       \
;     *(bf16x8*)((char*)K_lds + (b) * SHM_K + KSWZ(32 + sr, kc)) = sr_[i].ks1; } while (0)
; template <bool FAST> __device__ __forceinline__ void attn_dense_body(const bf16_t* __restrict__ Qb, const bf16_t* __restrict__ Kh, const bf16_t* __restrict__ Vh, ...
;     ...
;   const int sr = tid >> 4, sc = (tid & 15) * 8, vst0 = v_st(sr, sc), vst1 = v_st(32 + sr, sc);
;   const int vb0 = (int)(uintptr_t)V_lds + v_rd_base(lane);
;   struct { bf16x8 vs0, vs1, ks0, ks1; } sr_[2];
;   const unsigned voff = (unsigned)(sr * LDV + sc) * 2u, koff = (unsigned)(sr * LDKK + sc) * 2u;
;     ...
;   f32x16 pA0, pA1, pB0, pB1; float mnA, mnB, alA, alB; bf16x8 pa0, pa1, pa2, pa3; constexpr int NT = SEQ / KVBLK;
;   constexpr int SE = 0, SO = 1;
;   SLOAD(SE, 0); asm volatile("s_waitcnt vmcnt(0)" ::: "memory"); SWRITE(0, SE); __syncthreads();
	global_load_dwordx4 v[2:5], v[2:3], off offset:1024
	s_nop 0
	global_load_dwordx4 v[6:9], v[6:7], off offset:1024
	v_lshl_add_u64 v[50:51], s[8:9], 0, v[20:21]
	global_load_dwordx4 v[24:27], v20, s[8:9]
	s_mov_b32 s8, 0x8000
	v_add_co_u32_e32 v10, vcc, s8, v50
	v_lshrrev_b32_e32 v12, 2, v12
	s_nop 0
	v_addc_co_u32_e32 v11, vcc, 0, v51, vcc
	global_load_dwordx4 v[28:31], v[10:11], off
	v_and_b32_e32 v10, 0xfffff0, v13
	v_lshlrev_b32_e32 v11, 1, v13
	v_and_or_b32 v10, v11, 8, v10
	v_lshrrev_b32_e32 v11, 1, v13
	v_lshrrev_b32_e32 v10, 1, v10
	v_bfe_u32 v38, v1, 4, 2
	v_or_b32_e32 v10, v10, v12
	v_and_or_b32 v11, v11, 4, v38
	v_add_u32_e32 v13, 32, v13
	v_lshlrev_b32_e32 v10, 9, v10
	v_lshlrev_b32_e32 v11, 6, v11
	v_and_b32_e32 v16, 48, v16
	v_and_b32_e32 v38, 0xfffff0, v13
	v_lshlrev_b32_e32 v39, 1, v13
	v_or3_b32 v10, v10, v11, v16
	v_and_or_b32 v38, v39, 8, v38
	v_lshrrev_b32_e32 v38, 1, v38
	v_add_u32_e32 v217, 0, v10
	v_or_b32_e32 v12, v38, v12
	s_waitcnt vmcnt(0)
	v_lshlrev_b32_e32 v12, 9, v12
	v_or3_b32 v11, v12, v11, v16
	v_add_u32_e32 v218, 0, v11
	s_mov_b32 s8, 0x124000
	s_mov_b32 s16, 0x244000
	v_lshlrev_b32_e32 v1, 1, v1
	v_and_b32_e32 v1, 32, v1
	s_cmp_lg_u32 0, -1
	s_cselect_b32 s9, 0, 0
	s_lshl_b32 s3, s3, 1
	s_and_b32 s48, s3, 0x300
	s_waitcnt vmcnt(3)
	ds_write_b128 v217, v[2:5]
	v_or_b32_e32 v2, v14, v15
	v_and_b32_e32 v237, 8, v0
	v_lshlrev_b32_e32 v237, 4, v237
	v_and_b32_e32 v238, 0x80, v0
	v_add_u32_e32 v220, 0, v2
	v_xor_b32_e32 v220, v238, v220
	v_lshl_or_b32 v2, v13, 8, v14
	v_add_u32_e32 v222, 0, v2
	v_xor_b32_e32 v222, v238, v222
	v_or_b32_e32 v2, v17, v23
	v_add_u32_e32 v221, 0, v2
	v_xor_b32_e32 v221, v237, v221
	s_waitcnt vmcnt(2)
	ds_write_b128 v218, v[6:9]
	s_waitcnt vmcnt(1)
	ds_write_b128 v220, v[24:27] offset:32768
	s_waitcnt vmcnt(0)
	ds_write_b128 v222, v[28:31] offset:32768
	s_waitcnt lgkmcnt(0)
	s_barrier
; #define SLOAD(i, k0) do { const char* vb_ = (const char*)Vh + (size_t)(k0) * (LDV * 2); const char* kb_ = (const char*)Kh + (size_t)(k0) * (LDKK * 2); \
;     sr_[i].vs0 = *(const bf16x8*)(vb_ + voff); sr_[i].vs1 = *(const bf16x8*)(vb_ + 32 * LDV * 2 + voff); \
;     sr_[i].ks0 = *(const bf16x8*)(kb_ + koff); sr_[i].ks1 = *(const bf16x8*)(kb_ + 32 * LDKK * 2 + koff); } while (0)
; #define SWRITE(b, i) do { *(bf16x8*)((char*)V_lds + (b) * SHM_V + vst0) = sr_[i].vs0;          \
;     *(bf16x8*)((char*)V_lds + (b) * SHM_V + vst1) = sr_[i].vs1; int kc = sc * 2;               \
;     *(bf16x8*)((char*)K_lds + (b) * SHM_K + KSWZ(sr, kc)) = sr_[i].ks0;                       \
;     *(bf16x8*)((char*)K_lds + (b) * SHM_K + KSWZ(32 + sr, kc)) = sr_[i].ks1; } while (0)
; #define SWAIT() asm volatile("s_waitcnt vmcnt(4)" ::: "memory")
; __device__ __forceinline__ void qkt(f32x16& p0, f32x16& p1, const bf16_t* Ks, const bf16x8* qr, int r32, int hi) {
;   p0 = f32x16{}; p1 = f32x16{};
;   for (int d0 = 0; d0 < 8; ++d0) { int cb = (d0 * 16 + hi * 8) * 2;
;     bf16x8 b0 = *reinterpret_cast<const bf16x8*>((const char*)Ks + KSWZ(r32, cb));
;     bf16x8 b1 = *reinterpret_cast<const bf16x8*>((const char*)Ks + KSWZ(32 + r32, cb));
;     p0 = __builtin_amdgcn_mfma_f32_32x32x16_bf16(b0, qr[d0], p0, 0, 0, 0);
;     p1 = __builtin_amdgcn_mfma_f32_32x32x16_bf16(b1, qr[d0], p1, 0, 0, 0); }
; template <bool FAST> __device__ __forceinline__ void attn_dense_body(const bf16_t* __restrict__ Qb, const bf16_t* __restrict__ Kh, const bf16_t* __restrict__ Vh, ...
;     ...
;   SLOAD(SE, 0); asm volatile("s_waitcnt vmcnt(0)" ::: "memory"); SWRITE(0, SE); __syncthreads();
;   qkt(pA0, pA1, K_lds, qr, r32, hi); psm<FAST>(pA0, pA1, m_reg, mnA, alA);
;   SLOAD(SO, KVBLK); SLOAD(SE, 2 * KVBLK);
;   SWAIT(); SWRITE(1, SO); __syncthreads();
	ds_read_b128 v[2:5], v221 offset:32768
	ds_read_b128 v[24:27], v221 offset:40960
	s_waitcnt lgkmcnt(1)
	v_mfma_f32_32x32x16_bf16 v[2:17], v[2:5], v[144:147], 0
	s_waitcnt lgkmcnt(0)
	v_mfma_f32_32x32x16_bf16 v[66:81], v[24:27], v[144:147], 0
	v_or_b32_e32 v24, v32, v23
	v_add_u32_e32 v223, 0, v24
	v_xor_b32_e32 v223, v237, v223
	ds_read_b128 v[24:27], v223 offset:32768
	ds_read_b128 v[28:31], v223 offset:40960
	s_waitcnt lgkmcnt(1)
	v_mfma_f32_32x32x16_bf16 v[2:17], v[24:27], v[140:143], v[2:17]
	v_or_b32_e32 v24, v33, v23
	v_add_u32_e32 v219, 0, v24
	v_xor_b32_e32 v219, v237, v219
	s_waitcnt lgkmcnt(0)
	v_mfma_f32_32x32x16_bf16 v[66:81], v[28:31], v[140:143], v[66:81]
	ds_read_b128 v[24:27], v219 offset:32768
	ds_read_b128 v[28:31], v219 offset:40960
	s_waitcnt lgkmcnt(1)
	v_mfma_f32_32x32x16_bf16 v[2:17], v[24:27], v[136:139], v[2:17]
	v_or_b32_e32 v24, v34, v23
	v_add_u32_e32 v216, 0, v24
	v_xor_b32_e32 v216, v237, v216
	s_waitcnt lgkmcnt(0)
	v_mfma_f32_32x32x16_bf16 v[66:81], v[28:31], v[136:139], v[66:81]
	ds_read_b128 v[24:27], v216 offset:32768
	ds_read_b128 v[28:31], v216 offset:40960
	s_waitcnt lgkmcnt(1)
	v_mfma_f32_32x32x16_bf16 v[2:17], v[24:27], v[132:135], v[2:17]
	v_or_b32_e32 v24, v35, v23
	v_add_u32_e32 v215, 0, v24
	v_xor_b32_e32 v215, v237, v215
	s_waitcnt lgkmcnt(0)
	v_mfma_f32_32x32x16_bf16 v[66:81], v[28:31], v[132:135], v[66:81]
	ds_read_b128 v[24:27], v215 offset:32768
	ds_read_b128 v[28:31], v215 offset:40960
	s_waitcnt lgkmcnt(1)
	v_mfma_f32_32x32x16_bf16 v[2:17], v[24:27], v[128:131], v[2:17]
	v_or_b32_e32 v24, v36, v23
	v_add_u32_e32 v214, 0, v24
	v_xor_b32_e32 v214, v237, v214
	s_waitcnt lgkmcnt(0)
	v_mfma_f32_32x32x16_bf16 v[66:81], v[28:31], v[128:131], v[66:81]
	ds_read_b128 v[24:27], v214 offset:32768
	ds_read_b128 v[28:31], v214 offset:40960
	s_waitcnt lgkmcnt(1)
	v_mfma_f32_32x32x16_bf16 v[2:17], v[24:27], v[124:127], v[2:17]
	v_or_b32_e32 v24, v37, v23
	v_add_u32_e32 v213, 0, v24
	v_xor_b32_e32 v213, v237, v213
	v_or_b32_e32 v23, v45, v23
	v_add_u32_e32 v224, 0, v23
	v_xor_b32_e32 v224, v237, v224
	v_and_b32_e32 v23, 0xc0, v44
	v_and_or_b32 v23, v22, 24, v23
	v_and_b32_e32 v22, 0x100, v22
	s_waitcnt lgkmcnt(0)
	v_mfma_f32_32x32x16_bf16 v[66:81], v[28:31], v[124:127], v[66:81]
	ds_read_b128 v[24:27], v213 offset:32768
	ds_read_b128 v[28:31], v213 offset:40960
	v_or3_b32 v1, v23, v1, v22
	v_add_u32_e32 v180, s9, v1
	s_addk_i32 s9, 0x4000
	s_add_u32 s6, s46, s6
	s_addc_u32 s7, s47, s7
	v_lshl_add_u64 v[194:195], s[6:7], 0, v[20:21]
	s_waitcnt lgkmcnt(1)
	v_mfma_f32_32x32x16_bf16 v[2:17], v[24:27], v[120:123], v[2:17]
	v_add_co_u32_e32 v24, vcc, s8, v48
	s_mov_b32 s8, 0x1b4000
	s_nop 0
	v_addc_co_u32_e32 v25, vcc, 0, v49, vcc
	v_add_co_u32_e32 v32, vcc, s8, v48
	s_mov_b32 s8, 0x10000
	s_nop 0
	v_addc_co_u32_e32 v33, vcc, 0, v49, vcc
	v_add_co_u32_e32 v36, vcc, s8, v50
	s_mov_b32 s8, 0x18000
	s_nop 0
	v_addc_co_u32_e32 v37, vcc, 0, v51, vcc
	v_add_co_u32_e32 v40, vcc, s8, v50
	global_load_dwordx4 v[24:27], v[24:25], off offset:1024
	s_nop 0
	global_load_dwordx4 v[32:35], v[32:33], off offset:1024
	v_addc_co_u32_e32 v41, vcc, 0, v51, vcc
	global_load_dwordx4 v[36:39], v[36:37], off
	s_nop 0
	global_load_dwordx4 v[40:43], v[40:41], off
	s_waitcnt lgkmcnt(0)
	v_mfma_f32_32x32x16_bf16 v[66:81], v[28:31], v[120:123], v[66:81]
	ds_read_b128 v[28:31], v224 offset:32768
	ds_read_b128 v[44:47], v224 offset:40960
	s_add_u32 s6, s46, s22
	v_add_u32_e32 v115, s9, v1
	s_addc_u32 s7, s47, s20
	v_mov_b32_e32 v1, 0
	s_mov_b32 s8, 1
	s_waitcnt lgkmcnt(1)
	v_mfma_f32_32x32x16_bf16 v[2:17], v[28:31], v[116:119], v[2:17]
	v_lshl_add_u64 v[196:197], s[6:7], 0, v[18:19]
	v_mov_b32_e32 v18, 0
	v_mov_b32_e32 v19, v1
	v_mov_b32_e32 v20, v1
	v_mov_b32_e32 v21, v1
	v_mov_b32_e32 v22, v1
	v_mov_b32_e32 v23, v1
	s_nop 4
	v_exp_f32_e32 v229, v2
	v_add_co_u32_e32 v2, vcc, s16, v48
	v_exp_f32_e32 v230, v3
	s_nop 0
	v_addc_co_u32_e32 v3, vcc, 0, v49, vcc
	s_mov_b32 s16, 0x2d4000
	v_exp_f32_e32 v231, v4
	v_add_co_u32_e32 v4, vcc, s16, v48
	v_exp_f32_e32 v233, v5
	s_nop 0
	v_addc_co_u32_e32 v5, vcc, 0, v49, vcc
	s_mov_b32 s16, 0x20000
	global_load_dwordx4 v[148:151], v[2:3], off offset:1024
	global_load_dwordx4 v[152:155], v[4:5], off offset:1024
	v_add_co_u32_e32 v2, vcc, s16, v50
	s_mov_b32 s16, 0x28000
	s_nop 0
	v_addc_co_u32_e32 v3, vcc, 0, v51, vcc
	v_add_co_u32_e32 v4, vcc, s16, v50
	s_waitcnt lgkmcnt(0)
	v_mfma_f32_32x32x16_bf16 v[66:81], v[44:47], v[116:119], v[66:81]
	v_addc_co_u32_e32 v5, vcc, 0, v51, vcc
	global_load_dwordx4 v[156:159], v[2:3], off
	global_load_dwordx4 v[160:163], v[4:5], off
	v_exp_f32_e32 v234, v6
	v_exp_f32_e32 v236, v7
	v_exp_f32_e32 v232, v8
	v_exp_f32_e32 v235, v9
	v_exp_f32_e32 v199, v10
	v_exp_f32_e32 v200, v11
	v_exp_f32_e32 v201, v12
	v_exp_f32_e32 v227, v13
	v_exp_f32_e32 v198, v14
	v_exp_f32_e32 v225, v15
	v_exp_f32_e32 v226, v16
	v_exp_f32_e32 v228, v17
	s_waitcnt vmcnt(4)
	s_waitcnt vmcnt(7)
	ds_write_b128 v217, v[24:27] offset:16384
	s_waitcnt vmcnt(6)
	ds_write_b128 v218, v[32:35] offset:16384
	s_waitcnt vmcnt(5)
	ds_write_b128 v220, v[36:39] offset:49152
	s_waitcnt vmcnt(4)
	ds_write_b128 v222, v[40:43] offset:49152
	v_mov_b32_e32 v2, 0
	v_mov_b32_e32 v3, v1
	v_mov_b32_e32 v4, v1
	v_mov_b32_e32 v5, v1
	v_mov_b32_e32 v6, v1
	v_mov_b32_e32 v7, v1
	v_mov_b32_e32 v8, v1
	v_mov_b32_e32 v9, v1
	v_mov_b32_e32 v10, v1
	v_mov_b32_e32 v11, v1
	v_mov_b32_e32 v12, v1
	v_mov_b32_e32 v13, v1
	v_mov_b32_e32 v14, v1
	v_mov_b32_e32 v15, v1
	v_mov_b32_e32 v16, v1
	v_mov_b32_e32 v17, v1
	v_mov_b32_e32 v24, v1
	v_mov_b32_e32 v25, v1
	v_mov_b32_e32 v26, v1
	v_mov_b32_e32 v27, v1
	v_mov_b32_e32 v28, v1
	v_mov_b32_e32 v29, v1
	v_mov_b32_e32 v30, v1
	v_mov_b32_e32 v31, v1
	v_mov_b32_e32 v32, v1
	v_mov_b32_e32 v33, v1
	v_mov_b32_e32 v34, 0
	v_mov_b32_e32 v35, v1
	v_mov_b32_e32 v36, v1
	v_mov_b32_e32 v37, v1
	v_mov_b32_e32 v38, v1
	v_mov_b32_e32 v39, v1
	v_mov_b32_e32 v40, v1
	v_mov_b32_e32 v41, v1
	v_mov_b32_e32 v42, v1
	v_mov_b32_e32 v43, v1
	v_mov_b32_e32 v44, v1
	v_mov_b32_e32 v45, v1
	v_mov_b32_e32 v46, v1
	v_mov_b32_e32 v47, v1
	v_mov_b32_e32 v48, v1
	v_mov_b32_e32 v49, v1
	v_mov_b32_e32 v50, 0
	v_mov_b32_e32 v51, v1
	v_mov_b32_e32 v52, v1
	v_mov_b32_e32 v53, v1
	v_mov_b32_e32 v54, v1
	v_mov_b32_e32 v55, v1
	v_mov_b32_e32 v56, v1
	v_mov_b32_e32 v57, v1
	v_mov_b32_e32 v58, v1
	v_mov_b32_e32 v59, v1
	v_mov_b32_e32 v60, v1
	v_mov_b32_e32 v61, v1
	v_mov_b32_e32 v62, v1
	v_mov_b32_e32 v63, v1
	v_mov_b32_e32 v64, v1
	v_mov_b32_e32 v65, v1
	s_waitcnt lgkmcnt(0)
	s_barrier
	s_branch .LBB0_431
